# xattn: K staging loads overlap the V loads (private registers, counted wait); swa: pos load's LDS write deferred behind slope/Q loads
# speedup vs baseline: 1.0018x; 1.0004x over previous
.LBB0_297:
	s_or_b64 exec, exec, s[6:7]
	v_and_b32_e32 v145, 31, v8
	v_lshl_add_u32 v40, v145, 2, s92
	v_cmp_lt_i32_e32 vcc, s9, v1
	v_mad_u64_u32 v[42:43], s[6:7], v0, s93, v[40:41]
	s_waitcnt vmcnt(14)
	v_cndmask_b32_e32 v2, 0, v2, vcc
	v_mad_u64_u32 v[0:1], s[6:7], v1, s93, v[40:41]
	v_cmp_lt_i32_e32 vcc, s9, v3
	s_waitcnt vmcnt(0)
	ds_write_b128 v140, v[116:119]
	ds_write_b128 v141, v[120:123]
	ds_write_b128 v142, v[124:127]
	ds_write_b128 v143, v[128:131]
	ds_write_b32 v42, v38
	ds_write_b32 v0, v2
	v_cndmask_b32_e32 v2, 0, v4, vcc
	v_mad_u64_u32 v[0:1], s[6:7], v3, s93, v[40:41]
	v_cmp_lt_i32_e32 vcc, s9, v5
	ds_write_b32 v0, v2
	v_mad_u64_u32 v[0:1], s[6:7], v5, s93, v[40:41]
	v_cndmask_b32_e32 v2, 0, v9, vcc
	v_cmp_lt_i32_e32 vcc, s9, v14
	ds_write_b32 v0, v2
	v_mad_u64_u32 v[0:1], s[6:7], v14, s93, v[40:41]
	v_cndmask_b32_e32 v2, 0, v15, vcc
	v_cmp_lt_i32_e32 vcc, s9, v16
	ds_write_b32 v0, v2
	v_mad_u64_u32 v[0:1], s[6:7], v16, s93, v[40:41]
	v_cndmask_b32_e32 v2, 0, v17, vcc
	v_cmp_lt_i32_e32 vcc, s9, v18
	ds_write_b32 v0, v2
	v_mad_u64_u32 v[0:1], s[6:7], v18, s93, v[40:41]
	v_cndmask_b32_e32 v2, 0, v19, vcc
	v_cmp_lt_i32_e32 vcc, s9, v20
	ds_write_b32 v0, v2
	v_mad_u64_u32 v[0:1], s[6:7], v20, s93, v[40:41]
	v_cndmask_b32_e32 v2, 0, v21, vcc
	v_cmp_lt_i32_e32 vcc, s9, v22
	ds_write_b32 v0, v2
	v_mad_u64_u32 v[0:1], s[6:7], v22, s93, v[40:41]
	v_cndmask_b32_e32 v2, 0, v24, vcc
	v_cmp_lt_i32_e32 vcc, s9, v23
	ds_write_b32 v0, v2
	v_mad_u64_u32 v[0:1], s[6:7], v23, s93, v[40:41]
	v_cndmask_b32_e32 v2, 0, v25, vcc
	v_cmp_lt_i32_e32 vcc, s9, v26
	ds_write_b32 v0, v2
	v_mad_u64_u32 v[0:1], s[6:7], v26, s93, v[40:41]
	v_cndmask_b32_e32 v2, 0, v27, vcc
	v_cmp_lt_i32_e32 vcc, s9, v28
	ds_write_b32 v0, v2
	v_mad_u64_u32 v[0:1], s[6:7], v28, s93, v[40:41]
	v_cndmask_b32_e32 v2, 0, v29, vcc
	v_cmp_lt_i32_e32 vcc, s9, v30
	ds_write_b32 v0, v2
	v_mad_u64_u32 v[0:1], s[6:7], v30, s93, v[40:41]
	v_cndmask_b32_e32 v2, 0, v31, vcc
	v_cmp_lt_i32_e32 vcc, s9, v32
	ds_write_b32 v0, v2
	v_mad_u64_u32 v[0:1], s[6:7], v32, s93, v[40:41]
	v_cndmask_b32_e32 v2, 0, v33, vcc
	v_cmp_lt_i32_e32 vcc, s9, v34
	ds_write_b32 v0, v2
	v_mad_u64_u32 v[0:1], s[6:7], v34, s93, v[40:41]
	v_cndmask_b32_e32 v2, 0, v35, vcc
	ds_write_b32 v0, v2
	v_mad_u64_u32 v[0:1], s[6:7], v36, s93, v[40:41]
	v_cmp_lt_i32_e32 vcc, s9, v36
	s_movk_i32 s6, 0x100
	s_nop 0
	v_cndmask_b32_e32 v2, 0, v37, vcc
	v_cmp_gt_i32_e32 vcc, s6, v8
	ds_write_b32 v0, v2
	s_and_saveexec_b64 s[6:7], vcc
	s_cbranch_execz .LBB0_301
	v_add_u32_e32 v0, s8, v8
	v_cmp_lt_i32_e32 vcc, -1, v0
	v_mov_b32_e32 v44, 0
	s_and_saveexec_b64 s[8:9], vcc
	s_cbranch_execz .LBB0_300
	s_ashr_i32 s13, s11, 31
	s_add_u32 s12, s11, s10
	v_ashrrev_i32_e32 v9, 31, v8
	s_addc_u32 s13, s13, 0
	v_lshl_add_u64 v[0:1], s[12:13], 0, v[8:9]
	v_lshl_add_u64 v[0:1], v[0:1], 2, v[12:13]
	global_load_dword v44, v[0:1], off offset:-512
.LBB0_300:
	s_or_b64 exec, exec, s[8:9]
	v_lshl_add_u32 v45, v8, 2, 0
	v_add_u32_e32 v45, 0x11400, v45
.LBB0_301:
	s_or_b64 exec, exec, s[6:7]
	v_ashrrev_i32_e32 v0, 7, v8
	v_lshl_add_u32 v2, s5, 2, v0
	v_add_u32_e32 v0, 1, v2
	v_cvt_f32_i32_e32 v13, v0
	v_add_u32_e32 v0, s36, v2
	v_ashrrev_i32_e32 v1, 31, v0
	v_and_b32_e32 v146, 64, v8
	v_lshl_add_u64 v[0:1], v[0:1], 2, v[10:11]
	s_or_b32 s5, s10, s11
	v_lshlrev_b32_e32 v12, 6, v2
	global_load_dword v147, v[0:1], off
	v_or3_b32 v3, v146, s5, v145
	v_add_u32_e32 v0, 0xe00, v12
	v_ashrrev_i32_e32 v9, 31, v3
	v_ashrrev_i32_e32 v114, 8, v0
	v_ashrrev_i32_e32 v115, 31, v114
	v_alignbit_b32 v0, v9, v3, 8
	v_mad_u64_u32 v[0:1], s[6:7], v0, 49, v[114:115]
	v_bfe_u32 v5, v8, 5, 1
	v_mad_u32_u24 v1, v9, 49, v1
	v_lshlrev_b32_e32 v4, 3, v5
	v_and_b32_e32 v11, 0xc0, v12
	v_lshlrev_b64 v[0:1], 17, v[0:1]
	v_lshlrev_b32_e32 v2, 9, v3
	v_or_b32_e32 v10, v11, v4
	v_lshl_add_u64 v[0:1], v[112:113], 0, v[0:1]
	v_and_b32_e32 v166, 0x1fe00, v2
	v_lshl_add_u64 v[0:1], v[0:1], 0, v[166:167]
	v_lshlrev_b32_e32 v166, 1, v10
	v_lshl_add_u64 v[14:15], v[0:1], 0, v[166:167]
	global_load_dwordx4 v[0:3], v[14:15], off
	global_load_dwordx4 v[100:103], v[14:15], off offset:32
	global_load_dwordx4 v[104:107], v[14:15], off offset:64
	global_load_dwordx4 v[108:111], v[14:15], off offset:96
	v_and_b32_e32 v9, 0xff, v8
	v_ashrrev_i32_e32 v14, 4, v8
	v_mov_b32_e32 v8, s92
	v_and_b32_e32 v15, -16, v14
	v_mad_u32_u24 v16, v9, s93, v8
	v_lshl_add_u32 v19, v15, 2, v16
	s_waitcnt vmcnt(5)
	v_cmp_gt_i32_e32 vcc, 0x100, v208
	s_and_saveexec_b64 s[6:7], vcc
	ds_write_b32 v45, v44
	s_or_b64 exec, exec, s[6:7]
	s_waitcnt lgkmcnt(0)
	s_barrier
	v_lshlrev_b32_e32 v17, 1, v9
	ds_read2_b32 v[8:9], v19 offset1:1
	v_add_u32_e32 v18, 0, v17
	v_mul_lo_u32 v15, v15, s69
	v_add_u32_e32 v20, v18, v15
	v_add3_u32 v15, 0, v15, v17
	s_waitcnt lgkmcnt(0)
	ds_write_b16 v20, v8 offset:36864
	ds_write_b16_d16_hi v15, v8 offset:37384
	ds_write_b16 v15, v9 offset:37904
	ds_write_b16_d16_hi v15, v9 offset:38424
	ds_read2_b32 v[8:9], v19 offset0:2 offset1:3
	s_waitcnt lgkmcnt(0)
	ds_write_b16 v15, v8 offset:38944
	ds_write_b16_d16_hi v15, v8 offset:39464
	ds_write_b16 v15, v9 offset:39984
	ds_write_b16_d16_hi v15, v9 offset:40504
	ds_read2_b32 v[8:9], v19 offset0:4 offset1:5
	s_waitcnt lgkmcnt(0)
	ds_write_b16 v15, v8 offset:41024
	ds_write_b16_d16_hi v15, v8 offset:41544
	ds_write_b16 v15, v9 offset:42064
	ds_write_b16_d16_hi v15, v9 offset:42584
	ds_read2_b32 v[8:9], v19 offset0:6 offset1:7
	s_waitcnt lgkmcnt(0)
	ds_write_b16 v15, v8 offset:43104
	ds_write_b16_d16_hi v15, v8 offset:43624
	ds_write_b16 v15, v9 offset:44144
	ds_write_b16_d16_hi v15, v9 offset:44664
	ds_read2_b32 v[8:9], v19 offset0:8 offset1:9
	s_waitcnt lgkmcnt(0)
	ds_write_b16 v15, v8 offset:45184
	ds_write_b16_d16_hi v15, v8 offset:45704
	ds_write_b16 v15, v9 offset:46224
	ds_write_b16_d16_hi v15, v9 offset:46744
	ds_read2_b32 v[8:9], v19 offset0:10 offset1:11
	s_waitcnt lgkmcnt(0)
	ds_write_b16 v15, v8 offset:47264
	ds_write_b16_d16_hi v15, v8 offset:47784
	ds_write_b16 v15, v9 offset:48304
	ds_write_b16_d16_hi v15, v9 offset:48824
	ds_read2_b32 v[8:9], v19 offset0:12 offset1:13
	s_waitcnt lgkmcnt(0)
	ds_write_b16 v15, v8 offset:49344
	ds_write_b16_d16_hi v15, v8 offset:49864
	ds_write_b16 v15, v9 offset:50384
	ds_write_b16_d16_hi v15, v9 offset:50904
	ds_read_b32 v8, v19 offset:56
	s_waitcnt lgkmcnt(0)
	ds_write_b16 v15, v8 offset:51424
	ds_write_b16_d16_hi v15, v8 offset:51944
	v_or_b32_e32 v8, 15, v14
	v_lshl_add_u32 v9, v8, 2, v16
	ds_read_b32 v9, v9
	v_mul_lo_u32 v8, v8, s69
	v_add_u32_e32 v14, v18, v8
	v_add3_u32 v8, 0, v8, v17
	s_mov_b32 s6, 0x42fc0000
	s_waitcnt lgkmcnt(0)
	ds_write_b16_d16_hi v8, v9 offset:37384
	v_cmp_lt_f32_e32 vcc, s6, v13
	v_mov_b32_e32 v8, 0x42800000
	ds_write_b16 v14, v9 offset:36864
	v_cndmask_b32_e32 v8, 0, v8, vcc
	v_sub_f32_e32 v8, v8, v13
	v_exp_f32_e32 v8, v8
	v_not_b32_e32 v9, 63
	v_cndmask_b32_e32 v9, 0, v9, vcc
	s_cmp_lg_u32 s76, 0
	v_ldexp_f32 v117, v8, v9
	v_lshlrev_b32_e32 v9, 2, v5
	v_lshlrev_b32_e32 v5, 4, v5
	s_cselect_b64 s[6:7], -1, 0
	s_add_i32 s85, 0, 0x11400
	v_add_u32_e32 v148, 0, v5
	v_add_u32_e32 v149, s85, v5
	v_or_b32_e32 v5, 2, v9
	v_cmp_gt_u32_e64 s[14:15], v5, v145
	v_or_b32_e32 v5, 3, v9
	v_cmp_gt_u32_e64 s[18:19], v5, v145
	v_or_b32_e32 v5, 9, v9
	v_cmp_gt_u32_e64 s[26:27], v5, v145
	v_or_b32_e32 v5, 10, v9
	v_cmp_gt_u32_e64 s[30:31], v5, v145
	v_or_b32_e32 v5, 11, v9
	s_mov_b32 s33, s36
	v_cmp_gt_u32_e64 s[36:37], v5, v145
	v_or_b32_e32 v5, 17, v9
	v_cmp_gt_u32_e64 s[44:45], v5, v145
	v_or_b32_e32 v5, 18, v9
	v_cmp_gt_u32_e64 s[48:49], v5, v145
	v_or_b32_e32 v5, 19, v9
	v_cmp_gt_u32_e64 s[52:53], v5, v145
	v_or_b32_e32 v5, 25, v9
	v_add_u32_e32 v8, 0x1100, v12
	v_and_b32_e32 v13, 64, v214
	v_cmp_gt_u32_e64 s[60:61], v5, v145
	v_or_b32_e32 v5, 26, v9
	s_mov_b64 s[2:3], s[64:65]
	v_ashrrev_i32_e32 v118, 8, v8
	v_or_b32_e32 v8, v11, v9
	v_xor_b32_e32 v11, 32, v214
	v_add_u32_e32 v13, 64, v13
	v_cmp_gt_u32_e64 s[64:65], v5, v145
	v_or_b32_e32 v5, 27, v9
	v_cmp_lt_i32_e32 vcc, v11, v13
	v_ashrrev_i32_e32 v13, 31, v12
	v_cmp_gt_u32_e64 s[68:69], v5, v145
	v_or_b32_e32 v5, s76, v146
	v_lshl_add_u64 v[6:7], v[12:13], 1, v[6:7]
	v_or_b32_e32 v150, 8, v9
	v_or_b32_e32 v152, 16, v9
	v_or_b32_e32 v154, 24, v9
	v_cmp_eq_u32_e64 s[74:75], 0, v5
	v_mov_b32_e32 v5, v167
	v_cndmask_b32_e32 v11, v214, v11, vcc
	v_cmp_gt_u32_e64 s[8:9], v9, v145
	v_cmp_ge_u32_e32 vcc, v9, v145
	v_cmp_gt_u32_e64 s[22:23], v150, v145
	v_cmp_gt_u32_e64 s[40:41], v152, v145
	v_cmp_gt_u32_e64 s[56:57], v154, v145
	v_cmp_lt_u32_e64 s[72:73], v9, v145
	v_mul_u32_u24_e32 v9, 0x208, v145
	v_lshl_add_u64 v[6:7], v[6:7], 0, v[4:5]
	s_mov_b64 s[82:83], 0x21cc2800
	s_mov_b32 s0, s66
	s_mov_b64 s[78:79], s[62:63]
	s_mov_b32 s96, 0
	v_ashrrev_i32_e32 v119, 31, v118
	v_lshlrev_b32_e32 v144, 2, v11
	s_and_b64 s[10:11], s[6:7], s[8:9]
	s_and_b64 s[12:13], s[6:7], vcc
	s_and_b64 s[16:17], s[6:7], s[14:15]
	s_and_b64 s[20:21], s[6:7], s[18:19]
	v_lshl_add_u32 v151, v150, 2, s85
	s_and_b64 s[24:25], s[6:7], s[22:23]
	s_and_b64 s[28:29], s[6:7], s[26:27]
	s_and_b64 s[34:35], s[6:7], s[30:31]
	s_and_b64 s[38:39], s[6:7], s[36:37]
	v_lshl_add_u32 v153, v152, 2, s85
	s_and_b64 s[42:43], s[6:7], s[40:41]
	s_and_b64 s[46:47], s[6:7], s[44:45]
	s_and_b64 s[50:51], s[6:7], s[48:49]
	s_and_b64 s[54:55], s[6:7], s[52:53]
	v_lshl_add_u32 v155, v154, 2, s85
	s_and_b64 s[58:59], s[6:7], s[56:57]
	s_and_b64 s[62:63], s[6:7], s[60:61]
	s_and_b64 s[66:67], s[6:7], s[64:65]
	s_and_b64 s[70:71], s[6:7], s[68:69]
	v_lshl_add_u64 v[120:121], v[6:7], 0, s[82:83]
	v_add3_u32 v156, 0, v9, v4
	s_mov_b64 s[82:83], -1
	v_lshlrev_b32_e32 v122, 1, v10
	v_lshlrev_b32_e32 v124, 1, v8
	s_waitcnt lgkmcnt(0)
	s_barrier

.LBB0_305:
	s_mov_b64 s[6:7], s[62:63]
	s_load_dwordx2 s[14:15], s[6:7], 0xc0
	s_lshl_b32 s96, s37, 1
	v_mov_b32_e32 v4, v208
	s_mov_b64 s[8:9], 0x4b00000
	s_ashr_i32 s6, s5, 5
	v_lshlrev_b32_e32 v5, 4, v4
	s_lshl_b32 s7, s6, 8
	v_and_b32_e32 v166, 0x70, v5
	v_ashrrev_i32_e32 v5, 3, v4
	v_add_u32_e32 v6, s7, v5
	v_ashrrev_i32_e32 v7, 31, v6
	v_lshlrev_b64 v[6:7], 12, v[6:7]
	v_add_u32_e32 v10, 0, v166
	v_mad_u64_u32 v[12:13], s[10:11], v5, s94, v[10:11]
	v_add_u32_e32 v11, 0x200, v4
	v_ashrrev_i32_e32 v5, 3, v11
	v_add_u32_e32 v14, 0x400, v4
	v_and_b32_e32 v88, 31, v4
	s_lshl_b32 s6, s6, 11
	v_bfe_u32 v37, v4, 5, 1
	v_mov_b32_e32 v38, s92
	v_lshl_add_u32 v89, v37, 4, 0
	s_waitcnt lgkmcnt(0)
	v_mov_b32_e32 v64, s14
	v_mov_b32_e32 v65, s15
	v_lshl_add_u64 v[0:1], v[64:65], 0, s[96:97]
	v_lshl_add_u64 v[0:1], v[0:1], 0, s[8:9]
	s_lshl_b32 s8, s5, 3
	s_and_b32 s8, s8, 0xc0
	s_lshl_b32 s96, s8, 1
	v_lshl_add_u64 v[2:3], v[0:1], 0, s[96:97]
	v_lshl_add_u64 v[2:3], v[2:3], 0, v[166:167]
	v_lshl_add_u64 v[6:7], v[2:3], 0, v[6:7]
	s_mov_b32 s9, 0
	s_mov_b64 s[10:11], 0x40000
	v_mov_b32_e32 v132, v12
	global_load_dwordx4 v[116:119], v[6:7], off
	v_lshl_add_u64 v[6:7], v[6:7], 0, s[10:11]
	global_load_dwordx4 v[120:123], v[6:7], off
	v_lshl_add_u64 v[6:7], v[6:7], 0, s[10:11]
	global_load_dwordx4 v[124:127], v[6:7], off
	v_lshl_add_u64 v[6:7], v[6:7], 0, s[10:11]
	global_load_dwordx4 v[128:131], v[6:7], off
	v_add_u32_e32 v12, 0x600, v4
	v_ashrrev_i32_e32 v5, 5, v4
	v_add_u32_e32 v2, s7, v5
	v_ashrrev_i32_e32 v3, 31, v2
	v_lshlrev_b64 v[2:3], 12, v[2:3]
	v_lshl_add_u64 v[2:3], v[0:1], 0, v[2:3]
	v_lshlrev_b32_e32 v6, 2, v4
	v_lshl_add_u64 v[2:3], v[2:3], 0, s[96:97]
	v_and_b32_e32 v166, 0x7c, v6
	v_lshl_add_u64 v[2:3], v[2:3], 0, v[166:167]
	v_ashrrev_i32_e32 v7, 5, v11
	global_load_dword v6, v[2:3], off offset:512
	v_add_u32_e32 v2, s7, v7
	v_ashrrev_i32_e32 v3, 31, v2
	v_lshlrev_b64 v[2:3], 12, v[2:3]
	v_lshl_add_u64 v[2:3], v[0:1], 0, v[2:3]
	v_lshl_add_u64 v[2:3], v[2:3], 0, s[96:97]
	v_lshl_add_u64 v[2:3], v[2:3], 0, v[166:167]
	v_ashrrev_i32_e32 v9, 5, v14
	global_load_dword v8, v[2:3], off offset:512
	v_add_u32_e32 v2, s7, v9
	v_ashrrev_i32_e32 v3, 31, v2
	v_lshlrev_b64 v[2:3], 12, v[2:3]
	v_lshl_add_u64 v[2:3], v[0:1], 0, v[2:3]
	v_lshl_add_u64 v[2:3], v[2:3], 0, s[96:97]
	v_lshl_add_u64 v[2:3], v[2:3], 0, v[166:167]
	v_ashrrev_i32_e32 v11, 5, v12
	global_load_dword v10, v[2:3], off offset:512
	v_add_u32_e32 v2, s7, v11
	v_ashrrev_i32_e32 v3, 31, v2
	v_lshlrev_b64 v[2:3], 12, v[2:3]
	v_lshl_add_u64 v[2:3], v[0:1], 0, v[2:3]
	v_lshl_add_u64 v[2:3], v[2:3], 0, s[96:97]
	v_lshl_add_u64 v[2:3], v[2:3], 0, v[166:167]
	global_load_dword v12, v[2:3], off offset:512
	v_add_u32_e32 v2, 0x800, v4
	v_ashrrev_i32_e32 v13, 5, v2
	v_add_u32_e32 v2, s7, v13
	v_ashrrev_i32_e32 v3, 31, v2
	v_lshlrev_b64 v[2:3], 12, v[2:3]
	v_lshl_add_u64 v[2:3], v[0:1], 0, v[2:3]
	v_lshl_add_u64 v[2:3], v[2:3], 0, s[96:97]
	v_lshl_add_u64 v[2:3], v[2:3], 0, v[166:167]
	global_load_dword v14, v[2:3], off offset:512
	v_add_u32_e32 v2, 0xa00, v4
	v_ashrrev_i32_e32 v15, 5, v2
	v_add_u32_e32 v2, s7, v15
	v_ashrrev_i32_e32 v3, 31, v2
	v_lshlrev_b64 v[2:3], 12, v[2:3]
	v_lshl_add_u64 v[2:3], v[0:1], 0, v[2:3]
	v_lshl_add_u64 v[2:3], v[2:3], 0, s[96:97]
	v_lshl_add_u64 v[2:3], v[2:3], 0, v[166:167]
	global_load_dword v16, v[2:3], off offset:512
	v_add_u32_e32 v2, 0xc00, v4
	v_ashrrev_i32_e32 v17, 5, v2
	v_add_u32_e32 v2, s7, v17
	v_ashrrev_i32_e32 v3, 31, v2
	v_lshlrev_b64 v[2:3], 12, v[2:3]
	v_lshl_add_u64 v[2:3], v[0:1], 0, v[2:3]
	v_lshl_add_u64 v[2:3], v[2:3], 0, s[96:97]
	v_lshl_add_u64 v[2:3], v[2:3], 0, v[166:167]
	global_load_dword v18, v[2:3], off offset:512
	v_add_u32_e32 v2, 0xe00, v4
	v_ashrrev_i32_e32 v19, 5, v2
	v_add_u32_e32 v2, s7, v19
	v_ashrrev_i32_e32 v3, 31, v2
	v_lshlrev_b64 v[2:3], 12, v[2:3]
	v_lshl_add_u64 v[2:3], v[0:1], 0, v[2:3]
	v_lshl_add_u64 v[2:3], v[2:3], 0, s[96:97]
	v_lshl_add_u64 v[2:3], v[2:3], 0, v[166:167]
	global_load_dword v20, v[2:3], off offset:512
	v_add_u32_e32 v2, 0x1000, v4
	v_ashrrev_i32_e32 v21, 5, v2
	v_add_u32_e32 v2, s7, v21
	v_ashrrev_i32_e32 v3, 31, v2
	v_lshlrev_b64 v[2:3], 12, v[2:3]
	v_lshl_add_u64 v[2:3], v[0:1], 0, v[2:3]
	v_lshl_add_u64 v[2:3], v[2:3], 0, s[96:97]
	v_lshl_add_u64 v[2:3], v[2:3], 0, v[166:167]
	global_load_dword v22, v[2:3], off offset:512
	v_add_u32_e32 v2, 0x1200, v4
	v_ashrrev_i32_e32 v23, 5, v2
	v_add_u32_e32 v2, s7, v23
	v_ashrrev_i32_e32 v3, 31, v2
	v_lshlrev_b64 v[2:3], 12, v[2:3]
	v_lshl_add_u64 v[2:3], v[0:1], 0, v[2:3]
	v_lshl_add_u64 v[2:3], v[2:3], 0, s[96:97]
	v_lshl_add_u64 v[2:3], v[2:3], 0, v[166:167]
	global_load_dword v24, v[2:3], off offset:512
	v_add_u32_e32 v2, 0x1400, v4
	v_ashrrev_i32_e32 v25, 5, v2
	v_add_u32_e32 v2, s7, v25
	v_ashrrev_i32_e32 v3, 31, v2
	v_lshlrev_b64 v[2:3], 12, v[2:3]
	v_lshl_add_u64 v[2:3], v[0:1], 0, v[2:3]
	v_lshl_add_u64 v[2:3], v[2:3], 0, s[96:97]
	v_lshl_add_u64 v[2:3], v[2:3], 0, v[166:167]
	global_load_dword v26, v[2:3], off offset:512
	v_add_u32_e32 v2, 0x1600, v4
	v_ashrrev_i32_e32 v27, 5, v2
	v_add_u32_e32 v2, s7, v27
	v_ashrrev_i32_e32 v3, 31, v2
	v_lshlrev_b64 v[2:3], 12, v[2:3]
	v_lshl_add_u64 v[2:3], v[0:1], 0, v[2:3]
	v_lshl_add_u64 v[2:3], v[2:3], 0, s[96:97]
	v_lshl_add_u64 v[2:3], v[2:3], 0, v[166:167]
	global_load_dword v28, v[2:3], off offset:512
	v_add_u32_e32 v2, 0x1800, v4
	v_ashrrev_i32_e32 v29, 5, v2
	v_add_u32_e32 v2, s7, v29
	v_ashrrev_i32_e32 v3, 31, v2
	v_lshlrev_b64 v[2:3], 12, v[2:3]
	v_lshl_add_u64 v[2:3], v[0:1], 0, v[2:3]
	v_lshl_add_u64 v[2:3], v[2:3], 0, s[96:97]
	v_lshl_add_u64 v[2:3], v[2:3], 0, v[166:167]
	global_load_dword v30, v[2:3], off offset:512
	v_add_u32_e32 v2, 0x1a00, v4
	v_ashrrev_i32_e32 v31, 5, v2
	v_add_u32_e32 v2, s7, v31
	v_ashrrev_i32_e32 v3, 31, v2
	v_lshlrev_b64 v[2:3], 12, v[2:3]
	v_lshl_add_u64 v[2:3], v[0:1], 0, v[2:3]
	v_lshl_add_u64 v[2:3], v[2:3], 0, s[96:97]
	v_lshl_add_u64 v[2:3], v[2:3], 0, v[166:167]
	global_load_dword v32, v[2:3], off offset:512
	v_add_u32_e32 v2, 0x1c00, v4
	v_ashrrev_i32_e32 v33, 5, v2
	v_add_u32_e32 v2, s7, v33
	v_ashrrev_i32_e32 v3, 31, v2
	v_lshlrev_b64 v[2:3], 12, v[2:3]
	v_lshl_add_u64 v[2:3], v[0:1], 0, v[2:3]
	v_lshl_add_u64 v[2:3], v[2:3], 0, s[96:97]
	v_lshl_add_u64 v[2:3], v[2:3], 0, v[166:167]
	global_load_dword v34, v[2:3], off offset:512
	v_add_u32_e32 v2, 0x1e00, v4
	v_ashrrev_i32_e32 v35, 5, v2
	v_add_u32_e32 v2, s7, v35
	v_ashrrev_i32_e32 v3, 31, v2
	v_lshlrev_b64 v[2:3], 12, v[2:3]
	v_lshl_add_u64 v[0:1], v[0:1], 0, v[2:3]
	v_lshl_add_u64 v[0:1], v[0:1], 0, s[96:97]
	v_lshl_add_u64 v[0:1], v[0:1], 0, v[166:167]
	global_load_dword v36, v[0:1], off offset:512
	s_waitcnt vmcnt(16)
	ds_write_b128 v132, v[116:119]
	ds_write_b128 v132, v[120:123] offset:9216
	ds_write_b128 v132, v[124:127] offset:18432
	ds_write_b128 v132, v[128:131] offset:27648
	v_lshl_add_u32 v0, v88, 2, s92
	v_mad_u64_u32 v[2:3], s[10:11], v5, s93, v[0:1]
	s_waitcnt vmcnt(15)
	ds_write_b32 v2, v6
	v_mad_u64_u32 v[2:3], s[10:11], v7, s93, v[0:1]
	s_waitcnt vmcnt(14)
	ds_write_b32 v2, v8
	v_mad_u64_u32 v[2:3], s[10:11], v9, s93, v[0:1]
	s_waitcnt vmcnt(13)
	ds_write_b32 v2, v10
	v_mad_u64_u32 v[2:3], s[10:11], v11, s93, v[0:1]
	s_waitcnt vmcnt(12)
	ds_write_b32 v2, v12
	v_mad_u64_u32 v[2:3], s[10:11], v13, s93, v[0:1]
	s_waitcnt vmcnt(11)
	ds_write_b32 v2, v14
	v_mad_u64_u32 v[2:3], s[10:11], v15, s93, v[0:1]
	s_waitcnt vmcnt(10)
	ds_write_b32 v2, v16
	v_mad_u64_u32 v[2:3], s[10:11], v17, s93, v[0:1]
	s_waitcnt vmcnt(9)
	ds_write_b32 v2, v18
	v_mad_u64_u32 v[2:3], s[10:11], v19, s93, v[0:1]
	s_waitcnt vmcnt(8)
	ds_write_b32 v2, v20
	v_mad_u64_u32 v[2:3], s[10:11], v21, s93, v[0:1]
	s_waitcnt vmcnt(7)
	ds_write_b32 v2, v22
	v_mad_u64_u32 v[2:3], s[10:11], v23, s93, v[0:1]
	s_waitcnt vmcnt(6)
	ds_write_b32 v2, v24
	v_mad_u64_u32 v[2:3], s[10:11], v25, s93, v[0:1]
	s_lshl_b32 s7, s5, 8
	s_waitcnt vmcnt(5)
	ds_write_b32 v2, v26
	v_mad_u64_u32 v[2:3], s[10:11], v27, s93, v[0:1]
	s_and_b32 s7, s7, 0x700
	s_or_b32 s6, s6, s7
	v_lshlrev_b32_e32 v16, 2, v37
	v_mov_b32_e32 v17, 0xff800000
	s_waitcnt vmcnt(4)
	ds_write_b32 v2, v28
	v_mad_u64_u32 v[2:3], s[10:11], v29, s93, v[0:1]
	s_waitcnt vmcnt(3)
	ds_write_b32 v2, v30
	v_mad_u64_u32 v[2:3], s[10:11], v31, s93, v[0:1]
	s_waitcnt vmcnt(2)
	ds_write_b32 v2, v32
	v_mad_u64_u32 v[2:3], s[10:11], v33, s93, v[0:1]
	v_mad_u64_u32 v[0:1], s[10:11], v35, s93, v[0:1]
	v_or_b32_e32 v1, s6, v88
	s_waitcnt vmcnt(1)
	ds_write_b32 v2, v34
	v_and_or_b32 v2, s5, 24, v37
	v_lshlrev_b32_e32 v2, 4, v2
	s_waitcnt vmcnt(0)
	ds_write_b32 v0, v36
	v_ashrrev_i32_e32 v0, 1, v4
	v_and_b32_e32 v0, 0xffffffe0, v0
	v_add_u32_e32 v86, v1, v0
	v_ashrrev_i32_e32 v87, 31, v86
	v_alignbit_b32 v0, v87, v86, 8
	v_mad_u64_u32 v[0:1], s[6:7], v0, s77, v[64:65]
	v_lshlrev_b32_e32 v3, 9, v86
	v_mad_u32_u24 v1, v87, s77, v1
	v_and_b32_e32 v166, 0x1fe00, v3
	v_lshl_add_u64 v[0:1], v[0:1], 0, v[166:167]
	s_mov_b64 s[6:7], 0x74c2800
	v_mov_b32_e32 v3, v167
	v_lshl_add_u64 v[0:1], v[0:1], 0, s[6:7]
	v_lshl_add_u64 v[2:3], v[0:1], 0, v[2:3]
	s_mov_b64 s[6:7], 0x360000
	v_lshl_add_u64 v[6:7], v[2:3], 0, s[6:7]
	s_mov_b32 s6, 0x360000
	v_add_co_u32_e32 v2, vcc, s6, v2
	s_mov_b64 s[6:7], 0x380000
	s_nop 0
	v_addc_co_u32_e32 v3, vcc, 0, v3, vcc
	global_load_dwordx4 v[48:51], v[2:3], off
	global_load_dwordx4 v[52:55], v[6:7], off offset:32
	global_load_dwordx4 v[56:59], v[6:7], off offset:64
	global_load_dwordx4 v[60:63], v[6:7], off offset:96
	v_or_b32_e32 v2, s8, v16
	v_lshlrev_b32_e32 v166, 1, v2
	v_lshl_add_u64 v[0:1], v[0:1], 0, v[166:167]
	v_lshl_add_u64 v[2:3], v[0:1], 0, s[6:7]
	s_mov_b32 s6, 0x380000
	v_add_co_u32_e32 v0, vcc, s6, v0
	s_mov_b64 s[6:7], -1
	s_nop 0
	v_addc_co_u32_e32 v1, vcc, 0, v1, vcc
	global_load_dwordx2 v[84:85], v[0:1], off
	global_load_dwordx2 v[78:79], v[2:3], off offset:16
	global_load_dwordx2 v[76:77], v[2:3], off offset:32
	global_load_dwordx2 v[74:75], v[2:3], off offset:48
	global_load_dwordx2 v[72:73], v[2:3], off offset:64
	global_load_dwordx2 v[70:71], v[2:3], off offset:80
	global_load_dwordx2 v[68:69], v[2:3], off offset:96
	global_load_dwordx2 v[66:67], v[2:3], off offset:112
	v_and_b32_e32 v0, 0xff, v4
	v_ashrrev_i32_e32 v2, 4, v4
	v_and_b32_e32 v3, -16, v2
	v_mad_u32_u24 v4, v0, s93, v38
	v_lshl_add_u32 v7, v3, 2, v4
	s_waitcnt lgkmcnt(0)
	s_barrier
	v_lshlrev_b32_e32 v5, 1, v0
	ds_read2_b32 v[0:1], v7 offset1:1
	v_add_u32_e32 v6, 0, v5
	v_mul_lo_u32 v3, v3, s69
	v_add_u32_e32 v8, v6, v3
	v_add3_u32 v3, 0, v3, v5
	s_waitcnt lgkmcnt(0)
	ds_write_b16 v8, v0 offset:36864
	ds_write_b16_d16_hi v3, v0 offset:37384
	ds_write_b16 v3, v1 offset:37904
	ds_write_b16_d16_hi v3, v1 offset:38424
	ds_read2_b32 v[0:1], v7 offset0:2 offset1:3
	s_waitcnt lgkmcnt(0)
	ds_write_b16 v3, v0 offset:38944
	ds_write_b16_d16_hi v3, v0 offset:39464
	ds_write_b16 v3, v1 offset:39984
	ds_write_b16_d16_hi v3, v1 offset:40504
	ds_read2_b32 v[0:1], v7 offset0:4 offset1:5
	s_waitcnt lgkmcnt(0)
	ds_write_b16 v3, v0 offset:41024
	ds_write_b16_d16_hi v3, v0 offset:41544
	ds_write_b16 v3, v1 offset:42064
	ds_write_b16_d16_hi v3, v1 offset:42584
	ds_read2_b32 v[0:1], v7 offset0:6 offset1:7
	s_waitcnt lgkmcnt(0)
	ds_write_b16 v3, v0 offset:43104
	ds_write_b16_d16_hi v3, v0 offset:43624
	ds_write_b16 v3, v1 offset:44144
	ds_write_b16_d16_hi v3, v1 offset:44664
	ds_read2_b32 v[0:1], v7 offset0:8 offset1:9
	s_waitcnt lgkmcnt(0)
	ds_write_b16 v3, v0 offset:45184
	ds_write_b16_d16_hi v3, v0 offset:45704
	ds_write_b16 v3, v1 offset:46224
	ds_write_b16_d16_hi v3, v1 offset:46744
	ds_read2_b32 v[0:1], v7 offset0:10 offset1:11
	s_waitcnt lgkmcnt(0)
	ds_write_b16 v3, v0 offset:47264
	ds_write_b16_d16_hi v3, v0 offset:47784
	ds_write_b16 v3, v1 offset:48304
	ds_write_b16_d16_hi v3, v1 offset:48824
	ds_read2_b32 v[0:1], v7 offset0:12 offset1:13
	s_waitcnt lgkmcnt(0)
	ds_write_b16 v3, v0 offset:49344
	ds_write_b16_d16_hi v3, v0 offset:49864
	ds_write_b16 v3, v1 offset:50384
	ds_write_b16_d16_hi v3, v1 offset:50904
	ds_read_b32 v0, v7 offset:56
	s_waitcnt lgkmcnt(0)
	ds_write_b16 v3, v0 offset:51424
	ds_write_b16_d16_hi v3, v0 offset:51944
	v_or_b32_e32 v0, 15, v2
	v_lshl_add_u32 v1, v0, 2, v4
	ds_read_b32 v1, v1
	v_mul_lo_u32 v0, v0, s69
	v_add_u32_e32 v2, v6, v0
	v_add3_u32 v0, 0, v0, v5
	s_waitcnt lgkmcnt(0)
	ds_write_b16 v2, v1 offset:36864
	ds_write_b16_d16_hi v0, v1 offset:37384
	s_waitcnt lgkmcnt(0)
	s_barrier
